# adaLN GEMV inner loop software-pipelined: next k-chunk's 8 weight-row loads in flight during the current chunk's FMAs (two register sets)
# baseline (speedup 1.0000x reference)
; #define INP(k) input_ptr(args, (k))
; __global__ void __launch_bounds__(NTHR, 2) fwd(Args args) {
;     ...
;         for (int task = gw; task < 4 * GEMV_KS * 48; task += NGW) {
;             const int cc = task % 48, ks = (task / 48) & (GEMV_KS - 1), l = task / (48 * GEMV_KS); const int n0 = cc * 256 + lane * 4;
;             const float* wp = INP(I_ADAW) + ((size_t)l * D + ks * GEMV_KC) * MODW + n0;
;             f32x4 a0 = {0, 0, 0, 0}, a1 = a0, a2 = a0, a3 = a0, a4 = a0;
; #pragma unroll 8
;             for (int k = 0; k < GEMV_KC; ++k) { const f32x4 wv = __builtin_nontemporal_load((const f32x4*)(wp + (size_t)k * MODW)); const int kk = ks * GEMV_KC + k;
;                 a0 += wv * sl[kk]; a1 += wv * sl[D + kk]; a2 += wv * sl[2 * D + kk]; a3 += wv * sl[3 * D + kk]; a4 += wv * sl[4 * D + kk]; }
.LBB0_21:
	s_mul_hi_i32 s26, s24, 0x2aaaaaab
	s_ashr_i32 s27, s26, 3
	s_lshr_b32 s28, s26, 31
	s_ashr_i32 s26, s26, 8
	v_mov_b32_e32 v0, 4
	s_add_i32 s27, s27, s28
	s_add_i32 s26, s26, s28
	s_and_b32 s25, s27, 31
	v_readfirstlane_b32 s28, v0
	s_ashr_i32 s29, s28, 31
	s_lshl_b64 s[28:29], s[28:29], 3
	s_add_u32 s28, s0, s28
	s_addc_u32 s29, s1, s29
	s_load_dwordx2 s[28:29], s[28:29], 0x0
	s_mul_i32 s31, s26, 0x6000000
	s_mul_i32 s33, s25, 0x300000
	s_mul_hi_i32 s30, s26, 0x6000000
	s_add_u32 s31, s31, s33
	s_addc_u32 s30, s30, 0
	v_lshl_or_b32 v0, s24, 8, v40
	s_mul_i32 s33, s27, 0x3000
	v_subrev_u32_e32 v0, s33, v0
	s_waitcnt lgkmcnt(0)
	s_add_u32 s28, s28, s31
	v_ashrrev_i32_e32 v1, 31, v0
	s_addc_u32 s29, s29, s30
	v_lshl_add_u64 v[0:1], v[0:1], 2, s[28:29]
	s_lshl_b32 s28, s25, 8
	v_mov_b32_e32 v12, 0
	v_lshl_add_u64 v[24:25], v[0:1], 0, s[6:7]
	s_add_i32 s28, s28, 0
	s_mov_b32 s29, 0
	v_mov_b32_e32 v13, v12
	v_mov_b32_e32 v14, v12
	v_mov_b32_e32 v15, v12
	v_mov_b32_e32 v16, v12
	v_mov_b32_e32 v17, v12
	v_mov_b32_e32 v18, v12
	v_mov_b32_e32 v19, v12
	v_mov_b32_e32 v8, v12
	v_mov_b32_e32 v9, v12
	v_mov_b32_e32 v10, v12
	v_mov_b32_e32 v11, v12
	v_mov_b32_e32 v4, v12
	v_mov_b32_e32 v5, v12
	v_mov_b32_e32 v6, v12
	v_mov_b32_e32 v7, v12
	v_mov_b32_e32 v0, v12
	v_mov_b32_e32 v1, v12
	v_mov_b32_e32 v2, v12
	v_mov_b32_e32 v3, v12
	global_load_dwordx4 v[20:23], v[24:25], off nt
	v_add_co_u32_e32 v162, vcc, s16, v24
	s_nop 1
	v_addc_co_u32_e32 v163, vcc, -1, v25, vcc
	v_add_co_u32_e32 v164, vcc, s18, v24
	s_nop 1
	v_addc_co_u32_e32 v165, vcc, -1, v25, vcc
	v_add_co_u32_e32 v166, vcc, s19, v24
	s_nop 1
	v_addc_co_u32_e32 v167, vcc, -1, v25, vcc
	v_add_co_u32_e32 v168, vcc, s21, v24
	s_nop 1
	v_addc_co_u32_e32 v169, vcc, -1, v25, vcc
	v_add_co_u32_e32 v170, vcc, s22, v24
	s_nop 1
	v_addc_co_u32_e32 v171, vcc, 0, v25, vcc
	v_add_co_u32_e32 v172, vcc, s17, v24
	s_nop 1
	v_addc_co_u32_e32 v173, vcc, 0, v25, vcc
	v_add_co_u32_e32 v174, vcc, s23, v24
	s_nop 1
	v_addc_co_u32_e32 v175, vcc, 0, v25, vcc
	global_load_dwordx4 v[28:31], v[162:163], off nt
	global_load_dwordx4 v[32:35], v[164:165], off nt
	global_load_dwordx4 v[42:45], v[166:167], off nt
	global_load_dwordx4 v[46:49], v[168:169], off nt
	global_load_dwordx4 v[50:53], v[170:171], off nt
	global_load_dwordx4 v[54:57], v[172:173], off nt
	global_load_dwordx4 v[58:61], v[174:175], off nt
.Lgv_loop:
	v_lshl_add_u64 v[24:25], v[24:25], 0, s[8:9]
	global_load_dwordx4 v[120:123], v[24:25], off nt
	v_add_co_u32_e32 v162, vcc, s16, v24
	s_nop 1
	v_addc_co_u32_e32 v163, vcc, -1, v25, vcc
	v_add_co_u32_e32 v164, vcc, s18, v24
	s_nop 1
	v_addc_co_u32_e32 v165, vcc, -1, v25, vcc
	v_add_co_u32_e32 v166, vcc, s19, v24
	s_nop 1
	v_addc_co_u32_e32 v167, vcc, -1, v25, vcc
	v_add_co_u32_e32 v168, vcc, s21, v24
	s_nop 1
	v_addc_co_u32_e32 v169, vcc, -1, v25, vcc
	v_add_co_u32_e32 v170, vcc, s22, v24
	s_nop 1
	v_addc_co_u32_e32 v171, vcc, 0, v25, vcc
	v_add_co_u32_e32 v172, vcc, s17, v24
	s_nop 1
	v_addc_co_u32_e32 v173, vcc, 0, v25, vcc
	v_add_co_u32_e32 v174, vcc, s23, v24
	s_nop 1
	v_addc_co_u32_e32 v175, vcc, 0, v25, vcc
	global_load_dwordx4 v[128:131], v[162:163], off nt
	global_load_dwordx4 v[132:135], v[164:165], off nt
	global_load_dwordx4 v[142:145], v[166:167], off nt
	global_load_dwordx4 v[146:149], v[168:169], off nt
	global_load_dwordx4 v[150:153], v[170:171], off nt
	global_load_dwordx4 v[154:157], v[172:173], off nt
	global_load_dwordx4 v[158:161], v[174:175], off nt
	s_add_i32 s30, s28, s29
	s_add_i32 s31, s30, 0x14000
	s_add_i32 s33, s30, 0x16000
	s_add_i32 s34, s30, 0x18000
	s_add_i32 s35, s30, 0x1a000
	s_add_i32 s36, s30, 0x1c000
	s_add_i32 s37, s30, 0x14010
	s_add_i32 s38, s30, 0x16010
	s_add_i32 s39, s30, 0x18010
	s_add_i32 s40, s30, 0x1a010
	s_add_i32 s30, s30, 0x1c010
	v_mov_b32_e32 v26, s31
	v_mov_b32_e32 v86, s38
	v_mov_b32_e32 v90, s39
	v_mov_b32_e32 v94, s40
	v_mov_b32_e32 v98, s30
	v_mov_b32_e32 v27, s33
	v_mov_b32_e32 v36, s34
	v_mov_b32_e32 v37, s35
	v_mov_b32_e32 v39, s36
	v_mov_b32_e32 v41, s37
	ds_read_b128 v[62:65], v26
	ds_read_b128 v[66:69], v27
	ds_read_b128 v[70:73], v36
	ds_read_b128 v[74:77], v37
	ds_read_b128 v[78:81], v39
	ds_read_b128 v[82:85], v41
	ds_read_b128 v[86:89], v86
	ds_read_b128 v[90:93], v90
	ds_read_b128 v[94:97], v94
	ds_read_b128 v[98:101], v98
	s_waitcnt lgkmcnt(9)
	v_mov_b32_e32 v26, v65
	s_waitcnt lgkmcnt(8)
	v_mov_b32_e32 v36, v69
	s_waitcnt lgkmcnt(7)
	v_mov_b32_e32 v102, v73
	s_waitcnt lgkmcnt(6)
	v_mov_b32_e32 v104, v77
	s_waitcnt lgkmcnt(5)
	v_mov_b32_e32 v106, v81
	s_add_i32 s29, s29, 32
	s_waitcnt lgkmcnt(4)
	v_mov_b32_e32 v108, v85
	s_waitcnt lgkmcnt(3)
	v_mov_b32_e32 v110, v89
	s_waitcnt lgkmcnt(2)
	v_mov_b32_e32 v112, v93
	s_waitcnt lgkmcnt(1)
	v_mov_b32_e32 v114, v97
	s_waitcnt lgkmcnt(0)
	v_mov_b32_e32 v116, v101
	s_waitcnt vmcnt(14)
	v_pk_fma_f32 v[14:15], v[30:31], v[62:63], v[14:15] op_sel_hi:[1,0,1]
	v_pk_fma_f32 v[12:13], v[28:29], v[62:63], v[12:13] op_sel_hi:[1,0,1]
	v_pk_fma_f32 v[18:19], v[30:31], v[66:67], v[18:19] op_sel_hi:[1,0,1]
	v_pk_fma_f32 v[16:17], v[28:29], v[66:67], v[16:17] op_sel_hi:[1,0,1]
	v_pk_fma_f32 v[10:11], v[30:31], v[70:71], v[10:11] op_sel_hi:[1,0,1]
	v_pk_fma_f32 v[8:9], v[28:29], v[70:71], v[8:9] op_sel_hi:[1,0,1]
	v_pk_fma_f32 v[6:7], v[30:31], v[74:75], v[6:7] op_sel_hi:[1,0,1]
	v_pk_fma_f32 v[4:5], v[28:29], v[74:75], v[4:5] op_sel_hi:[1,0,1]
	v_pk_fma_f32 v[2:3], v[30:31], v[78:79], v[2:3] op_sel_hi:[1,0,1]
	v_pk_fma_f32 v[0:1], v[28:29], v[78:79], v[0:1] op_sel_hi:[1,0,1]
	s_waitcnt vmcnt(13)
; __global__ void __launch_bounds__(NTHR, 2) fwd(Args args) {
;     ...
;             for (int k = 0; k < GEMV_KC; ++k) { const f32x4 wv = __builtin_nontemporal_load((const f32x4*)(wp + (size_t)k * MODW)); const int kk = ks * GEMV_KC + k;
;                 a0 += wv * sl[kk]; a1 += wv * sl[D + kk]; a2 += wv * sl[2 * D + kk]; a3 += wv * sl[3 * D + kk]; a4 += wv * sl[4 * D + kk]; }
	v_pk_fma_f32 v[14:15], v[34:35], v[62:63], v[14:15] op_sel:[0,1,0]
	v_pk_fma_f32 v[12:13], v[32:33], v[62:63], v[12:13] op_sel:[0,1,0]
	v_pk_fma_f32 v[18:19], v[34:35], v[66:67], v[18:19] op_sel:[0,1,0]
	v_pk_fma_f32 v[16:17], v[32:33], v[66:67], v[16:17] op_sel:[0,1,0]
	v_pk_fma_f32 v[10:11], v[34:35], v[70:71], v[10:11] op_sel:[0,1,0]
	v_pk_fma_f32 v[8:9], v[32:33], v[70:71], v[8:9] op_sel:[0,1,0]
	v_pk_fma_f32 v[6:7], v[34:35], v[74:75], v[6:7] op_sel:[0,1,0]
	v_pk_fma_f32 v[4:5], v[32:33], v[74:75], v[4:5] op_sel:[0,1,0]
	v_pk_fma_f32 v[2:3], v[34:35], v[78:79], v[2:3] op_sel:[0,1,0]
	v_pk_fma_f32 v[0:1], v[32:33], v[78:79], v[0:1] op_sel:[0,1,0]
	s_waitcnt vmcnt(12)
	v_pk_fma_f32 v[14:15], v[44:45], v[64:65], v[14:15] op_sel_hi:[1,0,1]
	v_pk_fma_f32 v[12:13], v[42:43], v[64:65], v[12:13] op_sel_hi:[1,0,1]
	v_pk_fma_f32 v[18:19], v[44:45], v[68:69], v[18:19] op_sel_hi:[1,0,1]
	v_pk_fma_f32 v[16:17], v[42:43], v[68:69], v[16:17] op_sel_hi:[1,0,1]
	v_pk_fma_f32 v[10:11], v[44:45], v[72:73], v[10:11] op_sel_hi:[1,0,1]
	v_pk_fma_f32 v[8:9], v[42:43], v[72:73], v[8:9] op_sel_hi:[1,0,1]
	v_pk_fma_f32 v[6:7], v[44:45], v[76:77], v[6:7] op_sel_hi:[1,0,1]
	v_pk_fma_f32 v[4:5], v[42:43], v[76:77], v[4:5] op_sel_hi:[1,0,1]
	v_pk_fma_f32 v[2:3], v[44:45], v[80:81], v[2:3] op_sel_hi:[1,0,1]
	v_pk_fma_f32 v[0:1], v[42:43], v[80:81], v[0:1] op_sel_hi:[1,0,1]
	s_waitcnt vmcnt(11)
	v_pk_fma_f32 v[14:15], v[48:49], v[26:27], v[14:15] op_sel_hi:[1,0,1]
	v_pk_fma_f32 v[12:13], v[46:47], v[26:27], v[12:13] op_sel_hi:[1,0,1]
	v_pk_fma_f32 v[18:19], v[48:49], v[36:37], v[18:19] op_sel_hi:[1,0,1]
	v_pk_fma_f32 v[16:17], v[46:47], v[36:37], v[16:17] op_sel_hi:[1,0,1]
	v_pk_fma_f32 v[10:11], v[48:49], v[102:103], v[10:11] op_sel_hi:[1,0,1]
	v_pk_fma_f32 v[8:9], v[46:47], v[102:103], v[8:9] op_sel_hi:[1,0,1]
	v_pk_fma_f32 v[6:7], v[48:49], v[104:105], v[6:7] op_sel_hi:[1,0,1]
	v_pk_fma_f32 v[4:5], v[46:47], v[104:105], v[4:5] op_sel_hi:[1,0,1]
	v_pk_fma_f32 v[2:3], v[48:49], v[106:107], v[2:3] op_sel_hi:[1,0,1]
	v_pk_fma_f32 v[0:1], v[46:47], v[106:107], v[0:1] op_sel_hi:[1,0,1]
	v_pk_fma_f32 v[14:15], v[22:23], v[82:83], v[14:15] op_sel_hi:[1,0,1]
	v_pk_fma_f32 v[12:13], v[20:21], v[82:83], v[12:13] op_sel_hi:[1,0,1]
	v_pk_fma_f32 v[18:19], v[22:23], v[86:87], v[18:19] op_sel_hi:[1,0,1]
	v_pk_fma_f32 v[16:17], v[20:21], v[86:87], v[16:17] op_sel_hi:[1,0,1]
	v_pk_fma_f32 v[10:11], v[22:23], v[90:91], v[10:11] op_sel_hi:[1,0,1]
	v_pk_fma_f32 v[8:9], v[20:21], v[90:91], v[8:9] op_sel_hi:[1,0,1]
	v_pk_fma_f32 v[6:7], v[22:23], v[94:95], v[6:7] op_sel_hi:[1,0,1]
	v_pk_fma_f32 v[4:5], v[20:21], v[94:95], v[4:5] op_sel_hi:[1,0,1]
	v_pk_fma_f32 v[2:3], v[22:23], v[98:99], v[2:3] op_sel_hi:[1,0,1]
	v_pk_fma_f32 v[0:1], v[20:21], v[98:99], v[0:1] op_sel_hi:[1,0,1]
	s_waitcnt vmcnt(10)
	v_pk_fma_f32 v[14:15], v[52:53], v[82:83], v[14:15] op_sel:[0,1,0]
	v_pk_fma_f32 v[12:13], v[50:51], v[82:83], v[12:13] op_sel:[0,1,0]
	v_pk_fma_f32 v[18:19], v[52:53], v[86:87], v[18:19] op_sel:[0,1,0]
	v_pk_fma_f32 v[16:17], v[50:51], v[86:87], v[16:17] op_sel:[0,1,0]
	v_pk_fma_f32 v[10:11], v[52:53], v[90:91], v[10:11] op_sel:[0,1,0]
	v_pk_fma_f32 v[8:9], v[50:51], v[90:91], v[8:9] op_sel:[0,1,0]
	v_pk_fma_f32 v[6:7], v[52:53], v[94:95], v[6:7] op_sel:[0,1,0]
	v_pk_fma_f32 v[4:5], v[50:51], v[94:95], v[4:5] op_sel:[0,1,0]
	v_pk_fma_f32 v[2:3], v[52:53], v[98:99], v[2:3] op_sel:[0,1,0]
	v_pk_fma_f32 v[0:1], v[50:51], v[98:99], v[0:1] op_sel:[0,1,0]
	s_waitcnt vmcnt(9)
	v_pk_fma_f32 v[14:15], v[56:57], v[84:85], v[14:15] op_sel_hi:[1,0,1]
	v_pk_fma_f32 v[12:13], v[54:55], v[84:85], v[12:13] op_sel_hi:[1,0,1]
	v_pk_fma_f32 v[18:19], v[56:57], v[88:89], v[18:19] op_sel_hi:[1,0,1]
	v_pk_fma_f32 v[16:17], v[54:55], v[88:89], v[16:17] op_sel_hi:[1,0,1]
	v_pk_fma_f32 v[10:11], v[56:57], v[92:93], v[10:11] op_sel_hi:[1,0,1]
	v_pk_fma_f32 v[8:9], v[54:55], v[92:93], v[8:9] op_sel_hi:[1,0,1]
	v_pk_fma_f32 v[6:7], v[56:57], v[96:97], v[6:7] op_sel_hi:[1,0,1]
	v_pk_fma_f32 v[4:5], v[54:55], v[96:97], v[4:5] op_sel_hi:[1,0,1]
	v_pk_fma_f32 v[2:3], v[56:57], v[100:101], v[2:3] op_sel_hi:[1,0,1]
	v_pk_fma_f32 v[0:1], v[54:55], v[100:101], v[0:1] op_sel_hi:[1,0,1]
	s_waitcnt vmcnt(8)
	v_pk_fma_f32 v[14:15], v[60:61], v[108:109], v[14:15] op_sel_hi:[1,0,1]
	v_pk_fma_f32 v[12:13], v[58:59], v[108:109], v[12:13] op_sel_hi:[1,0,1]
	v_pk_fma_f32 v[18:19], v[60:61], v[110:111], v[18:19] op_sel_hi:[1,0,1]
	v_pk_fma_f32 v[16:17], v[58:59], v[110:111], v[16:17] op_sel_hi:[1,0,1]
	v_pk_fma_f32 v[10:11], v[60:61], v[112:113], v[10:11] op_sel_hi:[1,0,1]
	v_pk_fma_f32 v[8:9], v[58:59], v[112:113], v[8:9] op_sel_hi:[1,0,1]
	v_pk_fma_f32 v[6:7], v[60:61], v[114:115], v[6:7] op_sel_hi:[1,0,1]
	v_pk_fma_f32 v[4:5], v[58:59], v[114:115], v[4:5] op_sel_hi:[1,0,1]
	v_pk_fma_f32 v[2:3], v[60:61], v[116:117], v[2:3] op_sel_hi:[1,0,1]
	v_pk_fma_f32 v[0:1], v[58:59], v[116:117], v[0:1] op_sel_hi:[1,0,1]
	v_lshl_add_u64 v[24:25], v[24:25], 0, s[8:9]
	s_cmpk_eq_i32 s29, 0xe0
	s_cbranch_scc1 .Lgv_last
; #define INP(k) input_ptr(args, (k))
; __global__ void __launch_bounds__(NTHR, 2) fwd(Args args) {
;     ...
;         for (int task = gw; task < 4 * GEMV_KS * 48; task += NGW) {
;             const int cc = task % 48, ks = (task / 48) & (GEMV_KS - 1), l = task / (48 * GEMV_KS); const int n0 = cc * 256 + lane * 4;
;             const float* wp = INP(I_ADAW) + ((size_t)l * D + ks * GEMV_KC) * MODW + n0;
;             f32x4 a0 = {0, 0, 0, 0}, a1 = a0, a2 = a0, a3 = a0, a4 = a0;
; #pragma unroll 8
;             for (int k = 0; k < GEMV_KC; ++k) { const f32x4 wv = __builtin_nontemporal_load((const f32x4*)(wp + (size_t)k * MODW)); const int kk = ks * GEMV_KC + k;
;                 a0 += wv * sl[kk]; a1 += wv * sl[D + kk]; a2 += wv * sl[2 * D + kk]; a3 += wv * sl[3 * D + kk]; a4 += wv * sl[4 * D + kk]; }
	global_load_dwordx4 v[20:23], v[24:25], off nt
	v_add_co_u32_e32 v162, vcc, s16, v24
	s_nop 1
	v_addc_co_u32_e32 v163, vcc, -1, v25, vcc
	v_add_co_u32_e32 v164, vcc, s18, v24
	s_nop 1
	v_addc_co_u32_e32 v165, vcc, -1, v25, vcc
	v_add_co_u32_e32 v166, vcc, s19, v24
	s_nop 1
	v_addc_co_u32_e32 v167, vcc, -1, v25, vcc
	v_add_co_u32_e32 v168, vcc, s21, v24
	s_nop 1
	v_addc_co_u32_e32 v169, vcc, -1, v25, vcc
	v_add_co_u32_e32 v170, vcc, s22, v24
	s_nop 1
	v_addc_co_u32_e32 v171, vcc, 0, v25, vcc
	v_add_co_u32_e32 v172, vcc, s17, v24
	s_nop 1
	v_addc_co_u32_e32 v173, vcc, 0, v25, vcc
	v_add_co_u32_e32 v174, vcc, s23, v24
	s_nop 1
	v_addc_co_u32_e32 v175, vcc, 0, v25, vcc
	global_load_dwordx4 v[28:31], v[162:163], off nt
	global_load_dwordx4 v[32:35], v[164:165], off nt
	global_load_dwordx4 v[42:45], v[166:167], off nt
	global_load_dwordx4 v[46:49], v[168:169], off nt
	global_load_dwordx4 v[50:53], v[170:171], off nt
	global_load_dwordx4 v[54:57], v[172:173], off nt
	global_load_dwordx4 v[58:61], v[174:175], off nt
	s_add_i32 s30, s28, s29
	s_add_i32 s31, s30, 0x14000
	s_add_i32 s33, s30, 0x16000
	s_add_i32 s34, s30, 0x18000
	s_add_i32 s35, s30, 0x1a000
	s_add_i32 s36, s30, 0x1c000
	s_add_i32 s37, s30, 0x14010
	s_add_i32 s38, s30, 0x16010
	s_add_i32 s39, s30, 0x18010
	s_add_i32 s40, s30, 0x1a010
	s_add_i32 s30, s30, 0x1c010
	v_mov_b32_e32 v26, s31
	v_mov_b32_e32 v86, s38
	v_mov_b32_e32 v90, s39
	v_mov_b32_e32 v94, s40
	v_mov_b32_e32 v98, s30
	v_mov_b32_e32 v27, s33
	v_mov_b32_e32 v36, s34
	v_mov_b32_e32 v37, s35
	v_mov_b32_e32 v39, s36
	v_mov_b32_e32 v41, s37
	ds_read_b128 v[62:65], v26
	ds_read_b128 v[66:69], v27
	ds_read_b128 v[70:73], v36
	ds_read_b128 v[74:77], v37
	ds_read_b128 v[78:81], v39
	ds_read_b128 v[82:85], v41
	ds_read_b128 v[86:89], v86
	ds_read_b128 v[90:93], v90
	ds_read_b128 v[94:97], v94
	ds_read_b128 v[98:101], v98
	s_waitcnt lgkmcnt(9)
	v_mov_b32_e32 v26, v65
	s_waitcnt lgkmcnt(8)
	v_mov_b32_e32 v36, v69
	s_waitcnt lgkmcnt(7)
	v_mov_b32_e32 v102, v73
	s_waitcnt lgkmcnt(6)
	v_mov_b32_e32 v104, v77
	s_waitcnt lgkmcnt(5)
	v_mov_b32_e32 v106, v81
	s_add_i32 s29, s29, 32
	s_waitcnt lgkmcnt(4)
	v_mov_b32_e32 v108, v85
	s_waitcnt lgkmcnt(3)
	v_mov_b32_e32 v110, v89
	s_waitcnt lgkmcnt(2)
	v_mov_b32_e32 v112, v93
	s_waitcnt lgkmcnt(1)
	v_mov_b32_e32 v114, v97
	s_waitcnt lgkmcnt(0)
	v_mov_b32_e32 v116, v101
	s_waitcnt vmcnt(14)
	v_pk_fma_f32 v[14:15], v[130:131], v[62:63], v[14:15] op_sel_hi:[1,0,1]
	v_pk_fma_f32 v[12:13], v[128:129], v[62:63], v[12:13] op_sel_hi:[1,0,1]
	v_pk_fma_f32 v[18:19], v[130:131], v[66:67], v[18:19] op_sel_hi:[1,0,1]
	v_pk_fma_f32 v[16:17], v[128:129], v[66:67], v[16:17] op_sel_hi:[1,0,1]
	v_pk_fma_f32 v[10:11], v[130:131], v[70:71], v[10:11] op_sel_hi:[1,0,1]
	v_pk_fma_f32 v[8:9], v[128:129], v[70:71], v[8:9] op_sel_hi:[1,0,1]
	v_pk_fma_f32 v[6:7], v[130:131], v[74:75], v[6:7] op_sel_hi:[1,0,1]
	v_pk_fma_f32 v[4:5], v[128:129], v[74:75], v[4:5] op_sel_hi:[1,0,1]
	v_pk_fma_f32 v[2:3], v[130:131], v[78:79], v[2:3] op_sel_hi:[1,0,1]
	v_pk_fma_f32 v[0:1], v[128:129], v[78:79], v[0:1] op_sel_hi:[1,0,1]
	s_waitcnt vmcnt(13)
	v_pk_fma_f32 v[14:15], v[134:135], v[62:63], v[14:15] op_sel:[0,1,0]
	v_pk_fma_f32 v[12:13], v[132:133], v[62:63], v[12:13] op_sel:[0,1,0]
	v_pk_fma_f32 v[18:19], v[134:135], v[66:67], v[18:19] op_sel:[0,1,0]
	v_pk_fma_f32 v[16:17], v[132:133], v[66:67], v[16:17] op_sel:[0,1,0]
	v_pk_fma_f32 v[10:11], v[134:135], v[70:71], v[10:11] op_sel:[0,1,0]
	v_pk_fma_f32 v[8:9], v[132:133], v[70:71], v[8:9] op_sel:[0,1,0]
	v_pk_fma_f32 v[6:7], v[134:135], v[74:75], v[6:7] op_sel:[0,1,0]
	v_pk_fma_f32 v[4:5], v[132:133], v[74:75], v[4:5] op_sel:[0,1,0]
	v_pk_fma_f32 v[2:3], v[134:135], v[78:79], v[2:3] op_sel:[0,1,0]
	v_pk_fma_f32 v[0:1], v[132:133], v[78:79], v[0:1] op_sel:[0,1,0]
	s_waitcnt vmcnt(12)
	v_pk_fma_f32 v[14:15], v[144:145], v[64:65], v[14:15] op_sel_hi:[1,0,1]
	v_pk_fma_f32 v[12:13], v[142:143], v[64:65], v[12:13] op_sel_hi:[1,0,1]
	v_pk_fma_f32 v[18:19], v[144:145], v[68:69], v[18:19] op_sel_hi:[1,0,1]
	v_pk_fma_f32 v[16:17], v[142:143], v[68:69], v[16:17] op_sel_hi:[1,0,1]
	v_pk_fma_f32 v[10:11], v[144:145], v[72:73], v[10:11] op_sel_hi:[1,0,1]
	v_pk_fma_f32 v[8:9], v[142:143], v[72:73], v[8:9] op_sel_hi:[1,0,1]
	v_pk_fma_f32 v[6:7], v[144:145], v[76:77], v[6:7] op_sel_hi:[1,0,1]
	v_pk_fma_f32 v[4:5], v[142:143], v[76:77], v[4:5] op_sel_hi:[1,0,1]
	v_pk_fma_f32 v[2:3], v[144:145], v[80:81], v[2:3] op_sel_hi:[1,0,1]
	v_pk_fma_f32 v[0:1], v[142:143], v[80:81], v[0:1] op_sel_hi:[1,0,1]
	s_waitcnt vmcnt(11)
	v_pk_fma_f32 v[14:15], v[148:149], v[26:27], v[14:15] op_sel_hi:[1,0,1]
	v_pk_fma_f32 v[12:13], v[146:147], v[26:27], v[12:13] op_sel_hi:[1,0,1]
	v_pk_fma_f32 v[18:19], v[148:149], v[36:37], v[18:19] op_sel_hi:[1,0,1]
	v_pk_fma_f32 v[16:17], v[146:147], v[36:37], v[16:17] op_sel_hi:[1,0,1]
	v_pk_fma_f32 v[10:11], v[148:149], v[102:103], v[10:11] op_sel_hi:[1,0,1]
	v_pk_fma_f32 v[8:9], v[146:147], v[102:103], v[8:9] op_sel_hi:[1,0,1]
	v_pk_fma_f32 v[6:7], v[148:149], v[104:105], v[6:7] op_sel_hi:[1,0,1]
	v_pk_fma_f32 v[4:5], v[146:147], v[104:105], v[4:5] op_sel_hi:[1,0,1]
	v_pk_fma_f32 v[2:3], v[148:149], v[106:107], v[2:3] op_sel_hi:[1,0,1]
	v_pk_fma_f32 v[0:1], v[146:147], v[106:107], v[0:1] op_sel_hi:[1,0,1]
	v_pk_fma_f32 v[14:15], v[122:123], v[82:83], v[14:15] op_sel_hi:[1,0,1]
	v_pk_fma_f32 v[12:13], v[120:121], v[82:83], v[12:13] op_sel_hi:[1,0,1]
	v_pk_fma_f32 v[18:19], v[122:123], v[86:87], v[18:19] op_sel_hi:[1,0,1]
	v_pk_fma_f32 v[16:17], v[120:121], v[86:87], v[16:17] op_sel_hi:[1,0,1]
	v_pk_fma_f32 v[10:11], v[122:123], v[90:91], v[10:11] op_sel_hi:[1,0,1]
	v_pk_fma_f32 v[8:9], v[120:121], v[90:91], v[8:9] op_sel_hi:[1,0,1]
	v_pk_fma_f32 v[6:7], v[122:123], v[94:95], v[6:7] op_sel_hi:[1,0,1]
	v_pk_fma_f32 v[4:5], v[120:121], v[94:95], v[4:5] op_sel_hi:[1,0,1]
	v_pk_fma_f32 v[2:3], v[122:123], v[98:99], v[2:3] op_sel_hi:[1,0,1]
	v_pk_fma_f32 v[0:1], v[120:121], v[98:99], v[0:1] op_sel_hi:[1,0,1]
	s_waitcnt vmcnt(10)
; __global__ void __launch_bounds__(NTHR, 2) fwd(Args args) {
;     ...
;             for (int k = 0; k < GEMV_KC; ++k) { const f32x4 wv = __builtin_nontemporal_load((const f32x4*)(wp + (size_t)k * MODW)); const int kk = ks * GEMV_KC + k;
;                 a0 += wv * sl[kk]; a1 += wv * sl[D + kk]; a2 += wv * sl[2 * D + kk]; a3 += wv * sl[3 * D + kk]; a4 += wv * sl[4 * D + kk]; }
	v_pk_fma_f32 v[14:15], v[152:153], v[82:83], v[14:15] op_sel:[0,1,0]
	v_pk_fma_f32 v[12:13], v[150:151], v[82:83], v[12:13] op_sel:[0,1,0]
	v_pk_fma_f32 v[18:19], v[152:153], v[86:87], v[18:19] op_sel:[0,1,0]
	v_pk_fma_f32 v[16:17], v[150:151], v[86:87], v[16:17] op_sel:[0,1,0]
	v_pk_fma_f32 v[10:11], v[152:153], v[90:91], v[10:11] op_sel:[0,1,0]
	v_pk_fma_f32 v[8:9], v[150:151], v[90:91], v[8:9] op_sel:[0,1,0]
	v_pk_fma_f32 v[6:7], v[152:153], v[94:95], v[6:7] op_sel:[0,1,0]
	v_pk_fma_f32 v[4:5], v[150:151], v[94:95], v[4:5] op_sel:[0,1,0]
	v_pk_fma_f32 v[2:3], v[152:153], v[98:99], v[2:3] op_sel:[0,1,0]
	v_pk_fma_f32 v[0:1], v[150:151], v[98:99], v[0:1] op_sel:[0,1,0]
	s_waitcnt vmcnt(9)
	v_pk_fma_f32 v[14:15], v[156:157], v[84:85], v[14:15] op_sel_hi:[1,0,1]
	v_pk_fma_f32 v[12:13], v[154:155], v[84:85], v[12:13] op_sel_hi:[1,0,1]
	v_pk_fma_f32 v[18:19], v[156:157], v[88:89], v[18:19] op_sel_hi:[1,0,1]
	v_pk_fma_f32 v[16:17], v[154:155], v[88:89], v[16:17] op_sel_hi:[1,0,1]
	v_pk_fma_f32 v[10:11], v[156:157], v[92:93], v[10:11] op_sel_hi:[1,0,1]
	v_pk_fma_f32 v[8:9], v[154:155], v[92:93], v[8:9] op_sel_hi:[1,0,1]
	v_pk_fma_f32 v[6:7], v[156:157], v[96:97], v[6:7] op_sel_hi:[1,0,1]
	v_pk_fma_f32 v[4:5], v[154:155], v[96:97], v[4:5] op_sel_hi:[1,0,1]
	v_pk_fma_f32 v[2:3], v[156:157], v[100:101], v[2:3] op_sel_hi:[1,0,1]
	v_pk_fma_f32 v[0:1], v[154:155], v[100:101], v[0:1] op_sel_hi:[1,0,1]
	s_waitcnt vmcnt(8)
	v_pk_fma_f32 v[14:15], v[160:161], v[108:109], v[14:15] op_sel_hi:[1,0,1]
	v_pk_fma_f32 v[12:13], v[158:159], v[108:109], v[12:13] op_sel_hi:[1,0,1]
	v_pk_fma_f32 v[18:19], v[160:161], v[110:111], v[18:19] op_sel_hi:[1,0,1]
	v_pk_fma_f32 v[16:17], v[158:159], v[110:111], v[16:17] op_sel_hi:[1,0,1]
	v_pk_fma_f32 v[10:11], v[160:161], v[112:113], v[10:11] op_sel_hi:[1,0,1]
	v_pk_fma_f32 v[8:9], v[158:159], v[112:113], v[8:9] op_sel_hi:[1,0,1]
	v_pk_fma_f32 v[6:7], v[160:161], v[114:115], v[6:7] op_sel_hi:[1,0,1]
	v_pk_fma_f32 v[4:5], v[158:159], v[114:115], v[4:5] op_sel_hi:[1,0,1]
	v_pk_fma_f32 v[2:3], v[160:161], v[116:117], v[2:3] op_sel_hi:[1,0,1]
	v_pk_fma_f32 v[0:1], v[158:159], v[116:117], v[0:1] op_sel_hi:[1,0,1]
	s_branch .Lgv_loop
.Lgv_last:
	s_add_i32 s30, s28, s29
	s_add_i32 s31, s30, 0x14000
	s_add_i32 s33, s30, 0x16000
	s_add_i32 s34, s30, 0x18000
	s_add_i32 s35, s30, 0x1a000
	s_add_i32 s36, s30, 0x1c000
	s_add_i32 s37, s30, 0x14010
	s_add_i32 s38, s30, 0x16010
	s_add_i32 s39, s30, 0x18010
	s_add_i32 s40, s30, 0x1a010
	s_add_i32 s30, s30, 0x1c010
	v_mov_b32_e32 v26, s31
	v_mov_b32_e32 v86, s38
	v_mov_b32_e32 v90, s39
	v_mov_b32_e32 v94, s40
	v_mov_b32_e32 v98, s30
	v_mov_b32_e32 v27, s33
	v_mov_b32_e32 v36, s34
	v_mov_b32_e32 v37, s35
	v_mov_b32_e32 v39, s36
	v_mov_b32_e32 v41, s37
	ds_read_b128 v[62:65], v26
	ds_read_b128 v[66:69], v27
	ds_read_b128 v[70:73], v36
	ds_read_b128 v[74:77], v37
	ds_read_b128 v[78:81], v39
	ds_read_b128 v[82:85], v41
	ds_read_b128 v[86:89], v86
	ds_read_b128 v[90:93], v90
	ds_read_b128 v[94:97], v94
	ds_read_b128 v[98:101], v98
	s_waitcnt lgkmcnt(9)
	v_mov_b32_e32 v26, v65
	s_waitcnt lgkmcnt(8)
	v_mov_b32_e32 v36, v69
	s_waitcnt lgkmcnt(7)
	v_mov_b32_e32 v102, v73
	s_waitcnt lgkmcnt(6)
	v_mov_b32_e32 v104, v77
	s_waitcnt lgkmcnt(5)
	v_mov_b32_e32 v106, v81
	s_add_i32 s29, s29, 32
	s_waitcnt lgkmcnt(4)
	v_mov_b32_e32 v108, v85
	s_waitcnt lgkmcnt(3)
	v_mov_b32_e32 v110, v89
	s_waitcnt lgkmcnt(2)
	v_mov_b32_e32 v112, v93
	s_waitcnt lgkmcnt(1)
	v_mov_b32_e32 v114, v97
	s_waitcnt lgkmcnt(0)
	v_mov_b32_e32 v116, v101
	s_waitcnt vmcnt(6)
	v_pk_fma_f32 v[14:15], v[130:131], v[62:63], v[14:15] op_sel_hi:[1,0,1]
	v_pk_fma_f32 v[12:13], v[128:129], v[62:63], v[12:13] op_sel_hi:[1,0,1]
	v_pk_fma_f32 v[18:19], v[130:131], v[66:67], v[18:19] op_sel_hi:[1,0,1]
	v_pk_fma_f32 v[16:17], v[128:129], v[66:67], v[16:17] op_sel_hi:[1,0,1]
	v_pk_fma_f32 v[10:11], v[130:131], v[70:71], v[10:11] op_sel_hi:[1,0,1]
	v_pk_fma_f32 v[8:9], v[128:129], v[70:71], v[8:9] op_sel_hi:[1,0,1]
	v_pk_fma_f32 v[6:7], v[130:131], v[74:75], v[6:7] op_sel_hi:[1,0,1]
	v_pk_fma_f32 v[4:5], v[128:129], v[74:75], v[4:5] op_sel_hi:[1,0,1]
	v_pk_fma_f32 v[2:3], v[130:131], v[78:79], v[2:3] op_sel_hi:[1,0,1]
	v_pk_fma_f32 v[0:1], v[128:129], v[78:79], v[0:1] op_sel_hi:[1,0,1]
	s_waitcnt vmcnt(5)
	v_pk_fma_f32 v[14:15], v[134:135], v[62:63], v[14:15] op_sel:[0,1,0]
	v_pk_fma_f32 v[12:13], v[132:133], v[62:63], v[12:13] op_sel:[0,1,0]
	v_pk_fma_f32 v[18:19], v[134:135], v[66:67], v[18:19] op_sel:[0,1,0]
	v_pk_fma_f32 v[16:17], v[132:133], v[66:67], v[16:17] op_sel:[0,1,0]
	v_pk_fma_f32 v[10:11], v[134:135], v[70:71], v[10:11] op_sel:[0,1,0]
	v_pk_fma_f32 v[8:9], v[132:133], v[70:71], v[8:9] op_sel:[0,1,0]
	v_pk_fma_f32 v[6:7], v[134:135], v[74:75], v[6:7] op_sel:[0,1,0]
	v_pk_fma_f32 v[4:5], v[132:133], v[74:75], v[4:5] op_sel:[0,1,0]
	v_pk_fma_f32 v[2:3], v[134:135], v[78:79], v[2:3] op_sel:[0,1,0]
	v_pk_fma_f32 v[0:1], v[132:133], v[78:79], v[0:1] op_sel:[0,1,0]
	s_waitcnt vmcnt(4)
; __global__ void __launch_bounds__(NTHR, 2) fwd(Args args) {
;     ...
;             for (int k = 0; k < GEMV_KC; ++k) { const f32x4 wv = __builtin_nontemporal_load((const f32x4*)(wp + (size_t)k * MODW)); const int kk = ks * GEMV_KC + k;
;                 a0 += wv * sl[kk]; a1 += wv * sl[D + kk]; a2 += wv * sl[2 * D + kk]; a3 += wv * sl[3 * D + kk]; a4 += wv * sl[4 * D + kk]; }
;             float* pp = PART + ((size_t)(ks * 4 + l) * 5) * MODW + n0;
;             *(f32x4*)(pp) = a0; *(f32x4*)(pp + MODW) = a1; *(f32x4*)(pp + 2 * MODW) = a2; *(f32x4*)(pp + 3 * MODW) = a3; *(f32x4*)(pp + 4 * MODW) = a4;
;         }
	v_pk_fma_f32 v[14:15], v[144:145], v[64:65], v[14:15] op_sel_hi:[1,0,1]
	v_pk_fma_f32 v[12:13], v[142:143], v[64:65], v[12:13] op_sel_hi:[1,0,1]
	v_pk_fma_f32 v[18:19], v[144:145], v[68:69], v[18:19] op_sel_hi:[1,0,1]
	v_pk_fma_f32 v[16:17], v[142:143], v[68:69], v[16:17] op_sel_hi:[1,0,1]
	v_pk_fma_f32 v[10:11], v[144:145], v[72:73], v[10:11] op_sel_hi:[1,0,1]
	v_pk_fma_f32 v[8:9], v[142:143], v[72:73], v[8:9] op_sel_hi:[1,0,1]
	v_pk_fma_f32 v[6:7], v[144:145], v[76:77], v[6:7] op_sel_hi:[1,0,1]
	v_pk_fma_f32 v[4:5], v[142:143], v[76:77], v[4:5] op_sel_hi:[1,0,1]
	v_pk_fma_f32 v[2:3], v[144:145], v[80:81], v[2:3] op_sel_hi:[1,0,1]
	v_pk_fma_f32 v[0:1], v[142:143], v[80:81], v[0:1] op_sel_hi:[1,0,1]
	s_waitcnt vmcnt(3)
	v_pk_fma_f32 v[14:15], v[148:149], v[26:27], v[14:15] op_sel_hi:[1,0,1]
	v_pk_fma_f32 v[12:13], v[146:147], v[26:27], v[12:13] op_sel_hi:[1,0,1]
	v_pk_fma_f32 v[18:19], v[148:149], v[36:37], v[18:19] op_sel_hi:[1,0,1]
	v_pk_fma_f32 v[16:17], v[146:147], v[36:37], v[16:17] op_sel_hi:[1,0,1]
	v_pk_fma_f32 v[10:11], v[148:149], v[102:103], v[10:11] op_sel_hi:[1,0,1]
	v_pk_fma_f32 v[8:9], v[146:147], v[102:103], v[8:9] op_sel_hi:[1,0,1]
	v_pk_fma_f32 v[6:7], v[148:149], v[104:105], v[6:7] op_sel_hi:[1,0,1]
	v_pk_fma_f32 v[4:5], v[146:147], v[104:105], v[4:5] op_sel_hi:[1,0,1]
	v_pk_fma_f32 v[2:3], v[148:149], v[106:107], v[2:3] op_sel_hi:[1,0,1]
	v_pk_fma_f32 v[0:1], v[146:147], v[106:107], v[0:1] op_sel_hi:[1,0,1]
	v_pk_fma_f32 v[14:15], v[122:123], v[82:83], v[14:15] op_sel_hi:[1,0,1]
	v_pk_fma_f32 v[12:13], v[120:121], v[82:83], v[12:13] op_sel_hi:[1,0,1]
	v_pk_fma_f32 v[18:19], v[122:123], v[86:87], v[18:19] op_sel_hi:[1,0,1]
	v_pk_fma_f32 v[16:17], v[120:121], v[86:87], v[16:17] op_sel_hi:[1,0,1]
	v_pk_fma_f32 v[10:11], v[122:123], v[90:91], v[10:11] op_sel_hi:[1,0,1]
	v_pk_fma_f32 v[8:9], v[120:121], v[90:91], v[8:9] op_sel_hi:[1,0,1]
	v_pk_fma_f32 v[6:7], v[122:123], v[94:95], v[6:7] op_sel_hi:[1,0,1]
	v_pk_fma_f32 v[4:5], v[120:121], v[94:95], v[4:5] op_sel_hi:[1,0,1]
	v_pk_fma_f32 v[2:3], v[122:123], v[98:99], v[2:3] op_sel_hi:[1,0,1]
	v_pk_fma_f32 v[0:1], v[120:121], v[98:99], v[0:1] op_sel_hi:[1,0,1]
	s_waitcnt vmcnt(2)
	v_pk_fma_f32 v[14:15], v[152:153], v[82:83], v[14:15] op_sel:[0,1,0]
	v_pk_fma_f32 v[12:13], v[150:151], v[82:83], v[12:13] op_sel:[0,1,0]
	v_pk_fma_f32 v[18:19], v[152:153], v[86:87], v[18:19] op_sel:[0,1,0]
	v_pk_fma_f32 v[16:17], v[150:151], v[86:87], v[16:17] op_sel:[0,1,0]
	v_pk_fma_f32 v[10:11], v[152:153], v[90:91], v[10:11] op_sel:[0,1,0]
	v_pk_fma_f32 v[8:9], v[150:151], v[90:91], v[8:9] op_sel:[0,1,0]
	v_pk_fma_f32 v[6:7], v[152:153], v[94:95], v[6:7] op_sel:[0,1,0]
	v_pk_fma_f32 v[4:5], v[150:151], v[94:95], v[4:5] op_sel:[0,1,0]
	v_pk_fma_f32 v[2:3], v[152:153], v[98:99], v[2:3] op_sel:[0,1,0]
	v_pk_fma_f32 v[0:1], v[150:151], v[98:99], v[0:1] op_sel:[0,1,0]
	s_waitcnt vmcnt(1)
	v_pk_fma_f32 v[14:15], v[156:157], v[84:85], v[14:15] op_sel_hi:[1,0,1]
	v_pk_fma_f32 v[12:13], v[154:155], v[84:85], v[12:13] op_sel_hi:[1,0,1]
	v_pk_fma_f32 v[18:19], v[156:157], v[88:89], v[18:19] op_sel_hi:[1,0,1]
	v_pk_fma_f32 v[16:17], v[154:155], v[88:89], v[16:17] op_sel_hi:[1,0,1]
	v_pk_fma_f32 v[10:11], v[156:157], v[92:93], v[10:11] op_sel_hi:[1,0,1]
	v_pk_fma_f32 v[8:9], v[154:155], v[92:93], v[8:9] op_sel_hi:[1,0,1]
	v_pk_fma_f32 v[6:7], v[156:157], v[96:97], v[6:7] op_sel_hi:[1,0,1]
	v_pk_fma_f32 v[4:5], v[154:155], v[96:97], v[4:5] op_sel_hi:[1,0,1]
	v_pk_fma_f32 v[2:3], v[156:157], v[100:101], v[2:3] op_sel_hi:[1,0,1]
	v_pk_fma_f32 v[0:1], v[154:155], v[100:101], v[0:1] op_sel_hi:[1,0,1]
	s_waitcnt vmcnt(0)
	v_pk_fma_f32 v[14:15], v[160:161], v[108:109], v[14:15] op_sel_hi:[1,0,1]
	v_pk_fma_f32 v[12:13], v[158:159], v[108:109], v[12:13] op_sel_hi:[1,0,1]
	v_pk_fma_f32 v[18:19], v[160:161], v[110:111], v[18:19] op_sel_hi:[1,0,1]
	v_pk_fma_f32 v[16:17], v[158:159], v[110:111], v[16:17] op_sel_hi:[1,0,1]
	v_pk_fma_f32 v[10:11], v[160:161], v[112:113], v[10:11] op_sel_hi:[1,0,1]
	v_pk_fma_f32 v[8:9], v[158:159], v[112:113], v[8:9] op_sel_hi:[1,0,1]
	v_pk_fma_f32 v[6:7], v[160:161], v[114:115], v[6:7] op_sel_hi:[1,0,1]
	v_pk_fma_f32 v[4:5], v[158:159], v[114:115], v[4:5] op_sel_hi:[1,0,1]
	v_pk_fma_f32 v[2:3], v[160:161], v[116:117], v[2:3] op_sel_hi:[1,0,1]
	v_pk_fma_f32 v[0:1], v[158:159], v[116:117], v[0:1] op_sel_hi:[1,0,1]
	s_lshl_b32 s25, s25, 2
	s_mul_i32 s27, s27, 48
	s_add_i32 s25, s25, s26
	s_sub_i32 s27, s24, s27
	s_mul_i32 s26, s25, 5
	s_mul_i32 s25, s25, 0x3c000
	v_lshl_or_b32 v20, s27, 8, v40
	s_mul_hi_i32 s27, s26, 0xc000
	s_add_u32 s26, s13, s25
	v_ashrrev_i32_e32 v21, 31, v20
	s_addc_u32 s27, s15, s27
	v_lshl_add_u64 v[20:21], v[20:21], 2, s[26:27]
	global_store_dwordx4 v[20:21], v[12:15], off
	s_add_i32 s24, s24, s10
	s_cmpk_gt_i32 s24, 0x17ff
	v_add_co_u32_e32 v12, vcc, 0xc000, v20
	s_nop 1
	v_addc_co_u32_e32 v13, vcc, 0, v21, vcc
	global_store_dwordx4 v[12:13], v[16:19], off
	v_add_co_u32_e32 v12, vcc, 0x18000, v20
	s_nop 1
	v_addc_co_u32_e32 v13, vcc, 0, v21, vcc
	global_store_dwordx4 v[12:13], v[8:11], off
	s_nop 1
	v_add_co_u32_e32 v8, vcc, 0x24000, v20
	s_nop 1
	v_addc_co_u32_e32 v9, vcc, 0, v21, vcc
	global_store_dwordx4 v[8:9], v[4:7], off
	s_nop 1
	v_add_co_u32_e32 v4, vcc, 0x30000, v20
	s_nop 1
	v_addc_co_u32_e32 v5, vcc, 0, v21, vcc
	global_store_dwordx4 v[4:5], v[0:3], off
	s_cbranch_scc0 .LBB0_21
